# retScan prefix loop hand-pipelined: 6 chunks of loads in flight with counted vmcnt instead of one exposed load round trip per chunk
# speedup vs baseline: 1.0054x; 1.0054x over previous
.LBB0_86:
	s_or_b64 exec, exec, s[0:1]
	v_readlane_b32 s0, v242, 14
	v_readlane_b32 s1, v242, 15
	s_and_b64 s[0:1], s[0:1], exec
	s_cselect_b32 s0, 3, 6
	v_readlane_b32 s1, v242, 4
	s_lshl_b32 s0, s1, s0
	s_add_i32 s3, s2, s0
	s_mov_b64 s[0:1], s[12:13]
	s_barrier
	s_mov_b64 s[0:1], s[14:15]
	s_mov_b64 s[0:1], s[16:17]
	s_mov_b64 s[0:1], s[18:19]
	s_mov_b64 s[0:1], s[20:21]
	s_mov_b64 s[0:1], s[22:23]
	s_mov_b64 s[0:1], s[24:25]
	s_mov_b64 s[0:1], s[26:27]
	v_readlane_b32 s36, v243, 22
	v_readlane_b32 s37, v243, 23
	s_mov_b64 s[0:1], s[36:37]
	v_readlane_b32 s38, v243, 24
	v_readlane_b32 s39, v243, 25
	s_mov_b64 s[0:1], s[38:39]
	v_readlane_b32 s40, v243, 26
	v_readlane_b32 s41, v243, 27
	s_mov_b64 s[0:1], s[40:41]
	v_readlane_b32 s42, v243, 28
	v_readlane_b32 s43, v243, 29
	s_mov_b64 s[0:1], s[42:43]
	v_readlane_b32 s44, v243, 30
	v_readlane_b32 s45, v243, 31
	s_mov_b64 s[0:1], s[44:45]
	v_readlane_b32 s46, v243, 32
	v_readlane_b32 s47, v243, 33
	s_mov_b64 s[0:1], s[46:47]
	v_readlane_b32 s48, v243, 34
	v_readlane_b32 s49, v243, 35
	s_mov_b64 s[0:1], s[48:49]
	v_readlane_b32 s50, v243, 36
	v_readlane_b32 s51, v243, 37
	s_mov_b64 s[0:1], s[50:51]
	s_mov_b64 s[0:1], s[52:53]
	s_mov_b64 s[0:1], s[54:55]
	s_mov_b64 s[0:1], s[56:57]
	s_mov_b64 s[0:1], s[58:59]
	s_mov_b64 s[0:1], s[60:61]
	s_mov_b64 s[0:1], s[62:63]
	s_mov_b64 s[0:1], s[64:65]
	s_mov_b64 s[0:1], s[66:67]
	v_readlane_b32 s36, v243, 5
	v_readlane_b32 s37, v243, 6
	s_mov_b64 s[0:1], s[36:37]
	v_readlane_b32 s38, v243, 7
	v_readlane_b32 s39, v243, 8
	s_mov_b64 s[0:1], s[38:39]
	v_readlane_b32 s40, v243, 9
	v_readlane_b32 s41, v243, 10
	s_mov_b64 s[0:1], s[40:41]
	v_readlane_b32 s28, v243, 1
	v_readlane_b32 s42, v243, 11
	v_readlane_b32 s43, v243, 12
	v_readlane_b32 s29, v243, 2
	v_readlane_b32 s30, v243, 3
	v_readlane_b32 s31, v243, 4
	s_mov_b64 s[4:5], s[42:43]
	s_mov_b64 s[0:1], s[28:29]
	s_mov_b64 s[8:9], s[30:31]
	s_ashr_i32 s3, s3, 2
	s_bfe_u32 s10, s2, 0x10001
	s_and_b32 s8, s3, 3
	s_add_u32 s8, s98, s8
	s_addc_u32 s9, s99, 0
	s_lshl_b64 s[8:9], s[8:9], 2
	s_add_u32 s0, s0, s8
	v_mov_b32_e32 v2, v200
	s_addc_u32 s1, s1, s9
	global_load_dword v0, v1, s[0:1] offset:8
	global_load_dword v3, v1, s[0:1] offset:24
	s_cmp_eq_u32 s10, 0
	s_mul_hi_i32 s9, s3, 0x48000
	s_mul_i32 s8, s3, 0x48000
	s_cselect_b64 s[0:1], -1, 0
	s_bitcmp1_b32 s2, 0
	s_mul_i32 s28, s10, 0x1200
	s_cselect_b32 s10, 0x900, 0
	s_lshl_b64 s[2:3], s[8:9], 1
	s_add_u32 s2, s4, s2
	s_addc_u32 s3, s5, s3
	s_lshl_b32 s29, s28, 1
	s_add_u32 s2, s2, s29
	s_addc_u32 s3, s3, 0
	s_lshl_b32 s29, s10, 1
	s_add_u32 s2, s2, s29
	s_addc_u32 s3, s3, 0
	s_add_u32 s2, s2, 0x1200000
	s_addc_u32 s3, s3, 0
	s_lshl_b64 s[8:9], s[8:9], 2
	s_add_u32 s4, s4, s8
	s_addc_u32 s5, s5, s9
	s_lshl_b32 s8, s28, 2
	s_add_u32 s4, s4, s8
	s_addc_u32 s5, s5, 0
	s_lshl_b32 s8, s10, 2
	s_add_u32 s8, s4, s8
	s_addc_u32 s9, s5, 0
	v_cmp_gt_i32_e64 s[4:5], 64, v2
	v_lshlrev_b32_e32 v20, 2, v2
	v_add_u32_e32 v22, 0x800, v20
	v_mov_b32_e32 v30, 0
	s_mov_b32 s31, 0
	v_ashrrev_i32_e32 v21, 31, v20
	v_ashrrev_i32_e32 v23, 31, v22
	s_mov_b32 s30, 24
	v_mov_b32_e32 v31, v30
	v_mov_b32_e32 v26, v30
	v_mov_b32_e32 v27, v30
	v_mov_b32_e32 v24, v30
	v_mov_b32_e32 v25, v30
	v_mov_b32_e32 v28, v30
	v_mov_b32_e32 v29, v30
	s_movk_i32 s38, 0x1e00
	s_waitcnt vmcnt(0)
	v_cndmask_b32_e64 v0, v3, v0, s[0:1]
	v_mul_f32_e32 v0, 0x43000000, v0
	v_exp_f32_e32 v14, v0
	v_ashrrev_i32_e32 v3, 31, v2
	v_lshl_add_u64 v[16:17], v[2:3], 4, s[8:9]
	v_mov_b32_e32 v2, v1
	v_mov_b32_e32 v3, v1
	v_mov_b32_e32 v0, v1
	v_mov_b64_e32 v[4:5], v[2:3]
	v_mov_b32_e32 v18, v14
	v_mov_b32_e32 v19, v14
	v_mov_b64_e32 v[2:3], v[0:1]
	v_lshlrev_b32_e32 v16, 4, v200
	v_add_u32_e32 v17, 0x1000, v16
	v_add_u32_e32 v18, 0x2000, v16
	v_lshlrev_b32_e32 v19, 3, v200
	v_add_u32_e32 v20, 0x1000, v19
	v_mov_b32_e32 v15, v14
	v_mov_b32_e32 v24, 0
	v_mov_b32_e32 v25, 0
	v_mov_b32_e32 v26, 0
	v_mov_b32_e32 v27, 0
	v_mov_b32_e32 v28, 0
	v_mov_b32_e32 v29, 0
	v_mov_b32_e32 v30, 0
	v_mov_b32_e32 v31, 0
	v_mov_b32_e32 v32, 0
	v_mov_b32_e32 v33, 0
	v_mov_b32_e32 v34, 0
	v_mov_b32_e32 v35, 0
	s_and_b64 s[28:29], s[0:1], exec
	s_mov_b32 s30, 0xffff7000
	s_mov_b32 s31, 0xffffb800
	s_and_b64 s[28:29], s[0:1], exec
	s_cselect_b32 s30, 0x9000, s30
	s_cselect_b32 s31, 0x4800, s31
	s_cselect_b32 s10, 0, 31
	s_mul_i32 s28, s10, 0x9000
	s_add_u32 s8, s8, s28
	s_addc_u32 s9, s9, 0
	s_mul_i32 s28, s10, 0x4800
	s_add_u32 s2, s2, s28
	s_addc_u32 s3, s3, 0
	s_ashr_i32 s29, s30, 31
	s_cmp_lg_u64 s[4:5], 0
	s_cbranch_scc1 .Lmys_n3
	global_load_dwordx4 v[130:133], v16, s[8:9]
	global_load_dwordx4 v[134:137], v17, s[8:9]
	s_add_u32 s8, s8, s30
	s_addc_u32 s9, s9, s29
	global_load_dwordx4 v[142:145], v16, s[8:9]
	global_load_dwordx4 v[146:149], v17, s[8:9]
	s_add_u32 s8, s8, s30
	s_addc_u32 s9, s9, s29
	global_load_dwordx4 v[154:157], v16, s[8:9]
	global_load_dwordx4 v[158:161], v17, s[8:9]
	s_add_u32 s8, s8, s30
	s_addc_u32 s9, s9, s29
	global_load_dwordx4 v[166:169], v16, s[8:9]
	global_load_dwordx4 v[170:173], v17, s[8:9]
	s_add_u32 s8, s8, s30
	s_addc_u32 s9, s9, s29
	global_load_dwordx4 v[36:39], v16, s[8:9]
	global_load_dwordx4 v[40:43], v17, s[8:9]
	s_add_u32 s8, s8, s30
	s_addc_u32 s9, s9, s29
	global_load_dwordx4 v[52:55], v16, s[8:9]
	global_load_dwordx4 v[56:59], v17, s[8:9]
	s_add_u32 s8, s8, s30
	s_addc_u32 s9, s9, s29
	s_waitcnt vmcnt(10)
	v_cvt_pk_bf16_f32 v6, v24, v25
	v_cvt_pk_bf16_f32 v7, v26, v27
	v_cvt_pk_bf16_f32 v8, v28, v29
	v_cvt_pk_bf16_f32 v9, v30, v31
	global_store_dwordx2 v19, v[6:7], s[2:3]
	global_store_dwordx2 v19, v[8:9], s[2:3] offset:2048
	v_pk_fma_f32 v[24:25], v[14:15], v[24:25], v[130:131]
	v_pk_fma_f32 v[26:27], v[14:15], v[26:27], v[132:133]
	v_pk_fma_f32 v[28:29], v[14:15], v[28:29], v[134:135]
	v_pk_fma_f32 v[30:31], v[14:15], v[30:31], v[136:137]
	s_add_u32 s2, s2, s31
	s_addc_u32 s3, s3, s29
	global_load_dwordx4 v[130:133], v16, s[8:9]
	global_load_dwordx4 v[134:137], v17, s[8:9]
	s_add_u32 s8, s8, s30
	s_addc_u32 s9, s9, s29
	s_waitcnt vmcnt(12)
	v_cvt_pk_bf16_f32 v6, v24, v25
	v_cvt_pk_bf16_f32 v7, v26, v27
	v_cvt_pk_bf16_f32 v8, v28, v29
	v_cvt_pk_bf16_f32 v9, v30, v31
	global_store_dwordx2 v19, v[6:7], s[2:3]
	global_store_dwordx2 v19, v[8:9], s[2:3] offset:2048
	v_pk_fma_f32 v[24:25], v[14:15], v[24:25], v[142:143]
	v_pk_fma_f32 v[26:27], v[14:15], v[26:27], v[144:145]
	v_pk_fma_f32 v[28:29], v[14:15], v[28:29], v[146:147]
	v_pk_fma_f32 v[30:31], v[14:15], v[30:31], v[148:149]
	s_add_u32 s2, s2, s31
	s_addc_u32 s3, s3, s29
	global_load_dwordx4 v[142:145], v16, s[8:9]
	global_load_dwordx4 v[146:149], v17, s[8:9]
	s_add_u32 s8, s8, s30
	s_addc_u32 s9, s9, s29
	s_waitcnt vmcnt(14)
	v_cvt_pk_bf16_f32 v6, v24, v25
	v_cvt_pk_bf16_f32 v7, v26, v27
	v_cvt_pk_bf16_f32 v8, v28, v29
	v_cvt_pk_bf16_f32 v9, v30, v31
	global_store_dwordx2 v19, v[6:7], s[2:3]
	global_store_dwordx2 v19, v[8:9], s[2:3] offset:2048
	v_pk_fma_f32 v[24:25], v[14:15], v[24:25], v[154:155]
	v_pk_fma_f32 v[26:27], v[14:15], v[26:27], v[156:157]
	v_pk_fma_f32 v[28:29], v[14:15], v[28:29], v[158:159]
	v_pk_fma_f32 v[30:31], v[14:15], v[30:31], v[160:161]
	s_add_u32 s2, s2, s31
	s_addc_u32 s3, s3, s29
	global_load_dwordx4 v[154:157], v16, s[8:9]
	global_load_dwordx4 v[158:161], v17, s[8:9]
	s_add_u32 s8, s8, s30
	s_addc_u32 s9, s9, s29
	s_waitcnt vmcnt(16)
	v_cvt_pk_bf16_f32 v6, v24, v25
	v_cvt_pk_bf16_f32 v7, v26, v27
	v_cvt_pk_bf16_f32 v8, v28, v29
	v_cvt_pk_bf16_f32 v9, v30, v31
	global_store_dwordx2 v19, v[6:7], s[2:3]
	global_store_dwordx2 v19, v[8:9], s[2:3] offset:2048
	v_pk_fma_f32 v[24:25], v[14:15], v[24:25], v[166:167]
	v_pk_fma_f32 v[26:27], v[14:15], v[26:27], v[168:169]
	v_pk_fma_f32 v[28:29], v[14:15], v[28:29], v[170:171]
	v_pk_fma_f32 v[30:31], v[14:15], v[30:31], v[172:173]
	s_add_u32 s2, s2, s31
	s_addc_u32 s3, s3, s29
	global_load_dwordx4 v[166:169], v16, s[8:9]
	global_load_dwordx4 v[170:173], v17, s[8:9]
	s_add_u32 s8, s8, s30
	s_addc_u32 s9, s9, s29
	s_waitcnt vmcnt(18)
	v_cvt_pk_bf16_f32 v6, v24, v25
	v_cvt_pk_bf16_f32 v7, v26, v27
	v_cvt_pk_bf16_f32 v8, v28, v29
	v_cvt_pk_bf16_f32 v9, v30, v31
	global_store_dwordx2 v19, v[6:7], s[2:3]
	global_store_dwordx2 v19, v[8:9], s[2:3] offset:2048
	v_pk_fma_f32 v[24:25], v[14:15], v[24:25], v[36:37]
	v_pk_fma_f32 v[26:27], v[14:15], v[26:27], v[38:39]
	v_pk_fma_f32 v[28:29], v[14:15], v[28:29], v[40:41]
	v_pk_fma_f32 v[30:31], v[14:15], v[30:31], v[42:43]
	s_add_u32 s2, s2, s31
	s_addc_u32 s3, s3, s29
	global_load_dwordx4 v[36:39], v16, s[8:9]
	global_load_dwordx4 v[40:43], v17, s[8:9]
	s_add_u32 s8, s8, s30
	s_addc_u32 s9, s9, s29
	s_waitcnt vmcnt(20)
	v_cvt_pk_bf16_f32 v6, v24, v25
	v_cvt_pk_bf16_f32 v7, v26, v27
	v_cvt_pk_bf16_f32 v8, v28, v29
	v_cvt_pk_bf16_f32 v9, v30, v31
	global_store_dwordx2 v19, v[6:7], s[2:3]
	global_store_dwordx2 v19, v[8:9], s[2:3] offset:2048
	v_pk_fma_f32 v[24:25], v[14:15], v[24:25], v[52:53]
	v_pk_fma_f32 v[26:27], v[14:15], v[26:27], v[54:55]
	v_pk_fma_f32 v[28:29], v[14:15], v[28:29], v[56:57]
	v_pk_fma_f32 v[30:31], v[14:15], v[30:31], v[58:59]
	s_add_u32 s2, s2, s31
	s_addc_u32 s3, s3, s29
	global_load_dwordx4 v[52:55], v16, s[8:9]
	global_load_dwordx4 v[56:59], v17, s[8:9]
	s_add_u32 s8, s8, s30
	s_addc_u32 s9, s9, s29
	s_waitcnt vmcnt(20)
	v_cvt_pk_bf16_f32 v6, v24, v25
	v_cvt_pk_bf16_f32 v7, v26, v27
	v_cvt_pk_bf16_f32 v8, v28, v29
	v_cvt_pk_bf16_f32 v9, v30, v31
	global_store_dwordx2 v19, v[6:7], s[2:3]
	global_store_dwordx2 v19, v[8:9], s[2:3] offset:2048
	v_pk_fma_f32 v[24:25], v[14:15], v[24:25], v[130:131]
	v_pk_fma_f32 v[26:27], v[14:15], v[26:27], v[132:133]
	v_pk_fma_f32 v[28:29], v[14:15], v[28:29], v[134:135]
	v_pk_fma_f32 v[30:31], v[14:15], v[30:31], v[136:137]
	s_add_u32 s2, s2, s31
	s_addc_u32 s3, s3, s29
	global_load_dwordx4 v[130:133], v16, s[8:9]
	global_load_dwordx4 v[134:137], v17, s[8:9]
	s_add_u32 s8, s8, s30
	s_addc_u32 s9, s9, s29
	s_waitcnt vmcnt(20)
	v_cvt_pk_bf16_f32 v6, v24, v25
	v_cvt_pk_bf16_f32 v7, v26, v27
	v_cvt_pk_bf16_f32 v8, v28, v29
	v_cvt_pk_bf16_f32 v9, v30, v31
	global_store_dwordx2 v19, v[6:7], s[2:3]
	global_store_dwordx2 v19, v[8:9], s[2:3] offset:2048
	v_pk_fma_f32 v[24:25], v[14:15], v[24:25], v[142:143]
	v_pk_fma_f32 v[26:27], v[14:15], v[26:27], v[144:145]
	v_pk_fma_f32 v[28:29], v[14:15], v[28:29], v[146:147]
	v_pk_fma_f32 v[30:31], v[14:15], v[30:31], v[148:149]
	s_add_u32 s2, s2, s31
	s_addc_u32 s3, s3, s29
	global_load_dwordx4 v[142:145], v16, s[8:9]
	global_load_dwordx4 v[146:149], v17, s[8:9]
	s_add_u32 s8, s8, s30
	s_addc_u32 s9, s9, s29
	s_waitcnt vmcnt(20)
	v_cvt_pk_bf16_f32 v6, v24, v25
	v_cvt_pk_bf16_f32 v7, v26, v27
	v_cvt_pk_bf16_f32 v8, v28, v29
	v_cvt_pk_bf16_f32 v9, v30, v31
	global_store_dwordx2 v19, v[6:7], s[2:3]
	global_store_dwordx2 v19, v[8:9], s[2:3] offset:2048
	v_pk_fma_f32 v[24:25], v[14:15], v[24:25], v[154:155]
	v_pk_fma_f32 v[26:27], v[14:15], v[26:27], v[156:157]
	v_pk_fma_f32 v[28:29], v[14:15], v[28:29], v[158:159]
	v_pk_fma_f32 v[30:31], v[14:15], v[30:31], v[160:161]
	s_add_u32 s2, s2, s31
	s_addc_u32 s3, s3, s29
	global_load_dwordx4 v[154:157], v16, s[8:9]
	global_load_dwordx4 v[158:161], v17, s[8:9]
	s_add_u32 s8, s8, s30
	s_addc_u32 s9, s9, s29
	s_waitcnt vmcnt(20)
	v_cvt_pk_bf16_f32 v6, v24, v25
	v_cvt_pk_bf16_f32 v7, v26, v27
	v_cvt_pk_bf16_f32 v8, v28, v29
	v_cvt_pk_bf16_f32 v9, v30, v31
	global_store_dwordx2 v19, v[6:7], s[2:3]
	global_store_dwordx2 v19, v[8:9], s[2:3] offset:2048
	v_pk_fma_f32 v[24:25], v[14:15], v[24:25], v[166:167]
	v_pk_fma_f32 v[26:27], v[14:15], v[26:27], v[168:169]
	v_pk_fma_f32 v[28:29], v[14:15], v[28:29], v[170:171]
	v_pk_fma_f32 v[30:31], v[14:15], v[30:31], v[172:173]
	s_add_u32 s2, s2, s31
	s_addc_u32 s3, s3, s29
	global_load_dwordx4 v[166:169], v16, s[8:9]
	global_load_dwordx4 v[170:173], v17, s[8:9]
	s_add_u32 s8, s8, s30
	s_addc_u32 s9, s9, s29
	s_waitcnt vmcnt(20)
	v_cvt_pk_bf16_f32 v6, v24, v25
	v_cvt_pk_bf16_f32 v7, v26, v27
	v_cvt_pk_bf16_f32 v8, v28, v29
	v_cvt_pk_bf16_f32 v9, v30, v31
	global_store_dwordx2 v19, v[6:7], s[2:3]
	global_store_dwordx2 v19, v[8:9], s[2:3] offset:2048
	v_pk_fma_f32 v[24:25], v[14:15], v[24:25], v[36:37]
	v_pk_fma_f32 v[26:27], v[14:15], v[26:27], v[38:39]
	v_pk_fma_f32 v[28:29], v[14:15], v[28:29], v[40:41]
	v_pk_fma_f32 v[30:31], v[14:15], v[30:31], v[42:43]
	s_add_u32 s2, s2, s31
	s_addc_u32 s3, s3, s29
	global_load_dwordx4 v[36:39], v16, s[8:9]
	global_load_dwordx4 v[40:43], v17, s[8:9]
	s_add_u32 s8, s8, s30
	s_addc_u32 s9, s9, s29
	s_waitcnt vmcnt(20)
	v_cvt_pk_bf16_f32 v6, v24, v25
	v_cvt_pk_bf16_f32 v7, v26, v27
	v_cvt_pk_bf16_f32 v8, v28, v29
	v_cvt_pk_bf16_f32 v9, v30, v31
	global_store_dwordx2 v19, v[6:7], s[2:3]
	global_store_dwordx2 v19, v[8:9], s[2:3] offset:2048
	v_pk_fma_f32 v[24:25], v[14:15], v[24:25], v[52:53]
	v_pk_fma_f32 v[26:27], v[14:15], v[26:27], v[54:55]
	v_pk_fma_f32 v[28:29], v[14:15], v[28:29], v[56:57]
	v_pk_fma_f32 v[30:31], v[14:15], v[30:31], v[58:59]
	s_add_u32 s2, s2, s31
	s_addc_u32 s3, s3, s29
	global_load_dwordx4 v[52:55], v16, s[8:9]
	global_load_dwordx4 v[56:59], v17, s[8:9]
	s_add_u32 s8, s8, s30
	s_addc_u32 s9, s9, s29
	s_waitcnt vmcnt(20)
	v_cvt_pk_bf16_f32 v6, v24, v25
	v_cvt_pk_bf16_f32 v7, v26, v27
	v_cvt_pk_bf16_f32 v8, v28, v29
	v_cvt_pk_bf16_f32 v9, v30, v31
	global_store_dwordx2 v19, v[6:7], s[2:3]
	global_store_dwordx2 v19, v[8:9], s[2:3] offset:2048
	v_pk_fma_f32 v[24:25], v[14:15], v[24:25], v[130:131]
	v_pk_fma_f32 v[26:27], v[14:15], v[26:27], v[132:133]
	v_pk_fma_f32 v[28:29], v[14:15], v[28:29], v[134:135]
	v_pk_fma_f32 v[30:31], v[14:15], v[30:31], v[136:137]
	s_add_u32 s2, s2, s31
	s_addc_u32 s3, s3, s29
	global_load_dwordx4 v[130:133], v16, s[8:9]
	global_load_dwordx4 v[134:137], v17, s[8:9]
	s_add_u32 s8, s8, s30
	s_addc_u32 s9, s9, s29
	s_waitcnt vmcnt(20)
	v_cvt_pk_bf16_f32 v6, v24, v25
	v_cvt_pk_bf16_f32 v7, v26, v27
	v_cvt_pk_bf16_f32 v8, v28, v29
	v_cvt_pk_bf16_f32 v9, v30, v31
	global_store_dwordx2 v19, v[6:7], s[2:3]
	global_store_dwordx2 v19, v[8:9], s[2:3] offset:2048
	v_pk_fma_f32 v[24:25], v[14:15], v[24:25], v[142:143]
	v_pk_fma_f32 v[26:27], v[14:15], v[26:27], v[144:145]
	v_pk_fma_f32 v[28:29], v[14:15], v[28:29], v[146:147]
	v_pk_fma_f32 v[30:31], v[14:15], v[30:31], v[148:149]
	s_add_u32 s2, s2, s31
	s_addc_u32 s3, s3, s29
	global_load_dwordx4 v[142:145], v16, s[8:9]
	global_load_dwordx4 v[146:149], v17, s[8:9]
	s_add_u32 s8, s8, s30
	s_addc_u32 s9, s9, s29
	s_waitcnt vmcnt(20)
	v_cvt_pk_bf16_f32 v6, v24, v25
	v_cvt_pk_bf16_f32 v7, v26, v27
	v_cvt_pk_bf16_f32 v8, v28, v29
	v_cvt_pk_bf16_f32 v9, v30, v31
	global_store_dwordx2 v19, v[6:7], s[2:3]
	global_store_dwordx2 v19, v[8:9], s[2:3] offset:2048
	v_pk_fma_f32 v[24:25], v[14:15], v[24:25], v[154:155]
	v_pk_fma_f32 v[26:27], v[14:15], v[26:27], v[156:157]
	v_pk_fma_f32 v[28:29], v[14:15], v[28:29], v[158:159]
	v_pk_fma_f32 v[30:31], v[14:15], v[30:31], v[160:161]
	s_add_u32 s2, s2, s31
	s_addc_u32 s3, s3, s29
	global_load_dwordx4 v[154:157], v16, s[8:9]
	global_load_dwordx4 v[158:161], v17, s[8:9]
	s_add_u32 s8, s8, s30
	s_addc_u32 s9, s9, s29
	s_waitcnt vmcnt(20)
	v_cvt_pk_bf16_f32 v6, v24, v25
	v_cvt_pk_bf16_f32 v7, v26, v27
	v_cvt_pk_bf16_f32 v8, v28, v29
	v_cvt_pk_bf16_f32 v9, v30, v31
	global_store_dwordx2 v19, v[6:7], s[2:3]
	global_store_dwordx2 v19, v[8:9], s[2:3] offset:2048
	v_pk_fma_f32 v[24:25], v[14:15], v[24:25], v[166:167]
	v_pk_fma_f32 v[26:27], v[14:15], v[26:27], v[168:169]
	v_pk_fma_f32 v[28:29], v[14:15], v[28:29], v[170:171]
	v_pk_fma_f32 v[30:31], v[14:15], v[30:31], v[172:173]
	s_add_u32 s2, s2, s31
	s_addc_u32 s3, s3, s29
	global_load_dwordx4 v[166:169], v16, s[8:9]
	global_load_dwordx4 v[170:173], v17, s[8:9]
	s_add_u32 s8, s8, s30
	s_addc_u32 s9, s9, s29
	s_waitcnt vmcnt(20)
	v_cvt_pk_bf16_f32 v6, v24, v25
	v_cvt_pk_bf16_f32 v7, v26, v27
	v_cvt_pk_bf16_f32 v8, v28, v29
	v_cvt_pk_bf16_f32 v9, v30, v31
	global_store_dwordx2 v19, v[6:7], s[2:3]
	global_store_dwordx2 v19, v[8:9], s[2:3] offset:2048
	v_pk_fma_f32 v[24:25], v[14:15], v[24:25], v[36:37]
	v_pk_fma_f32 v[26:27], v[14:15], v[26:27], v[38:39]
	v_pk_fma_f32 v[28:29], v[14:15], v[28:29], v[40:41]
	v_pk_fma_f32 v[30:31], v[14:15], v[30:31], v[42:43]
	s_add_u32 s2, s2, s31
	s_addc_u32 s3, s3, s29
	global_load_dwordx4 v[36:39], v16, s[8:9]
	global_load_dwordx4 v[40:43], v17, s[8:9]
	s_add_u32 s8, s8, s30
	s_addc_u32 s9, s9, s29
	s_waitcnt vmcnt(20)
	v_cvt_pk_bf16_f32 v6, v24, v25
	v_cvt_pk_bf16_f32 v7, v26, v27
	v_cvt_pk_bf16_f32 v8, v28, v29
	v_cvt_pk_bf16_f32 v9, v30, v31
	global_store_dwordx2 v19, v[6:7], s[2:3]
	global_store_dwordx2 v19, v[8:9], s[2:3] offset:2048
	v_pk_fma_f32 v[24:25], v[14:15], v[24:25], v[52:53]
	v_pk_fma_f32 v[26:27], v[14:15], v[26:27], v[54:55]
	v_pk_fma_f32 v[28:29], v[14:15], v[28:29], v[56:57]
	v_pk_fma_f32 v[30:31], v[14:15], v[30:31], v[58:59]
	s_add_u32 s2, s2, s31
	s_addc_u32 s3, s3, s29
	global_load_dwordx4 v[52:55], v16, s[8:9]
	global_load_dwordx4 v[56:59], v17, s[8:9]
	s_add_u32 s8, s8, s30
	s_addc_u32 s9, s9, s29
	s_waitcnt vmcnt(20)
	v_cvt_pk_bf16_f32 v6, v24, v25
	v_cvt_pk_bf16_f32 v7, v26, v27
	v_cvt_pk_bf16_f32 v8, v28, v29
	v_cvt_pk_bf16_f32 v9, v30, v31
	global_store_dwordx2 v19, v[6:7], s[2:3]
	global_store_dwordx2 v19, v[8:9], s[2:3] offset:2048
	v_pk_fma_f32 v[24:25], v[14:15], v[24:25], v[130:131]
	v_pk_fma_f32 v[26:27], v[14:15], v[26:27], v[132:133]
	v_pk_fma_f32 v[28:29], v[14:15], v[28:29], v[134:135]
	v_pk_fma_f32 v[30:31], v[14:15], v[30:31], v[136:137]
	s_add_u32 s2, s2, s31
	s_addc_u32 s3, s3, s29
	global_load_dwordx4 v[130:133], v16, s[8:9]
	global_load_dwordx4 v[134:137], v17, s[8:9]
	s_add_u32 s8, s8, s30
	s_addc_u32 s9, s9, s29
	s_waitcnt vmcnt(20)
	v_cvt_pk_bf16_f32 v6, v24, v25
	v_cvt_pk_bf16_f32 v7, v26, v27
	v_cvt_pk_bf16_f32 v8, v28, v29
	v_cvt_pk_bf16_f32 v9, v30, v31
	global_store_dwordx2 v19, v[6:7], s[2:3]
	global_store_dwordx2 v19, v[8:9], s[2:3] offset:2048
	v_pk_fma_f32 v[24:25], v[14:15], v[24:25], v[142:143]
	v_pk_fma_f32 v[26:27], v[14:15], v[26:27], v[144:145]
	v_pk_fma_f32 v[28:29], v[14:15], v[28:29], v[146:147]
	v_pk_fma_f32 v[30:31], v[14:15], v[30:31], v[148:149]
	s_add_u32 s2, s2, s31
	s_addc_u32 s3, s3, s29
	global_load_dwordx4 v[142:145], v16, s[8:9]
	global_load_dwordx4 v[146:149], v17, s[8:9]
	s_add_u32 s8, s8, s30
	s_addc_u32 s9, s9, s29
	s_waitcnt vmcnt(20)
	v_cvt_pk_bf16_f32 v6, v24, v25
	v_cvt_pk_bf16_f32 v7, v26, v27
	v_cvt_pk_bf16_f32 v8, v28, v29
	v_cvt_pk_bf16_f32 v9, v30, v31
	global_store_dwordx2 v19, v[6:7], s[2:3]
	global_store_dwordx2 v19, v[8:9], s[2:3] offset:2048
	v_pk_fma_f32 v[24:25], v[14:15], v[24:25], v[154:155]
	v_pk_fma_f32 v[26:27], v[14:15], v[26:27], v[156:157]
	v_pk_fma_f32 v[28:29], v[14:15], v[28:29], v[158:159]
	v_pk_fma_f32 v[30:31], v[14:15], v[30:31], v[160:161]
	s_add_u32 s2, s2, s31
	s_addc_u32 s3, s3, s29
	global_load_dwordx4 v[154:157], v16, s[8:9]
	global_load_dwordx4 v[158:161], v17, s[8:9]
	s_add_u32 s8, s8, s30
	s_addc_u32 s9, s9, s29
	s_waitcnt vmcnt(20)
	v_cvt_pk_bf16_f32 v6, v24, v25
	v_cvt_pk_bf16_f32 v7, v26, v27
	v_cvt_pk_bf16_f32 v8, v28, v29
	v_cvt_pk_bf16_f32 v9, v30, v31
	global_store_dwordx2 v19, v[6:7], s[2:3]
	global_store_dwordx2 v19, v[8:9], s[2:3] offset:2048
	v_pk_fma_f32 v[24:25], v[14:15], v[24:25], v[166:167]
	v_pk_fma_f32 v[26:27], v[14:15], v[26:27], v[168:169]
	v_pk_fma_f32 v[28:29], v[14:15], v[28:29], v[170:171]
	v_pk_fma_f32 v[30:31], v[14:15], v[30:31], v[172:173]
	s_add_u32 s2, s2, s31
	s_addc_u32 s3, s3, s29
	global_load_dwordx4 v[166:169], v16, s[8:9]
	global_load_dwordx4 v[170:173], v17, s[8:9]
	s_add_u32 s8, s8, s30
	s_addc_u32 s9, s9, s29
	s_waitcnt vmcnt(20)
	v_cvt_pk_bf16_f32 v6, v24, v25
	v_cvt_pk_bf16_f32 v7, v26, v27
	v_cvt_pk_bf16_f32 v8, v28, v29
	v_cvt_pk_bf16_f32 v9, v30, v31
	global_store_dwordx2 v19, v[6:7], s[2:3]
	global_store_dwordx2 v19, v[8:9], s[2:3] offset:2048
	v_pk_fma_f32 v[24:25], v[14:15], v[24:25], v[36:37]
	v_pk_fma_f32 v[26:27], v[14:15], v[26:27], v[38:39]
	v_pk_fma_f32 v[28:29], v[14:15], v[28:29], v[40:41]
	v_pk_fma_f32 v[30:31], v[14:15], v[30:31], v[42:43]
	s_add_u32 s2, s2, s31
	s_addc_u32 s3, s3, s29
	global_load_dwordx4 v[36:39], v16, s[8:9]
	global_load_dwordx4 v[40:43], v17, s[8:9]
	s_add_u32 s8, s8, s30
	s_addc_u32 s9, s9, s29
	s_waitcnt vmcnt(20)
	v_cvt_pk_bf16_f32 v6, v24, v25
	v_cvt_pk_bf16_f32 v7, v26, v27
	v_cvt_pk_bf16_f32 v8, v28, v29
	v_cvt_pk_bf16_f32 v9, v30, v31
	global_store_dwordx2 v19, v[6:7], s[2:3]
	global_store_dwordx2 v19, v[8:9], s[2:3] offset:2048
	v_pk_fma_f32 v[24:25], v[14:15], v[24:25], v[52:53]
	v_pk_fma_f32 v[26:27], v[14:15], v[26:27], v[54:55]
	v_pk_fma_f32 v[28:29], v[14:15], v[28:29], v[56:57]
	v_pk_fma_f32 v[30:31], v[14:15], v[30:31], v[58:59]
	s_add_u32 s2, s2, s31
	s_addc_u32 s3, s3, s29
	global_load_dwordx4 v[52:55], v16, s[8:9]
	global_load_dwordx4 v[56:59], v17, s[8:9]
	s_add_u32 s8, s8, s30
	s_addc_u32 s9, s9, s29
	s_waitcnt vmcnt(20)
	v_cvt_pk_bf16_f32 v6, v24, v25
	v_cvt_pk_bf16_f32 v7, v26, v27
	v_cvt_pk_bf16_f32 v8, v28, v29
	v_cvt_pk_bf16_f32 v9, v30, v31
	global_store_dwordx2 v19, v[6:7], s[2:3]
	global_store_dwordx2 v19, v[8:9], s[2:3] offset:2048
	v_pk_fma_f32 v[24:25], v[14:15], v[24:25], v[130:131]
	v_pk_fma_f32 v[26:27], v[14:15], v[26:27], v[132:133]
	v_pk_fma_f32 v[28:29], v[14:15], v[28:29], v[134:135]
	v_pk_fma_f32 v[30:31], v[14:15], v[30:31], v[136:137]
	s_add_u32 s2, s2, s31
	s_addc_u32 s3, s3, s29
	global_load_dwordx4 v[130:133], v16, s[8:9]
	global_load_dwordx4 v[134:137], v17, s[8:9]
	s_add_u32 s8, s8, s30
	s_addc_u32 s9, s9, s29
	s_waitcnt vmcnt(20)
	v_cvt_pk_bf16_f32 v6, v24, v25
	v_cvt_pk_bf16_f32 v7, v26, v27
	v_cvt_pk_bf16_f32 v8, v28, v29
	v_cvt_pk_bf16_f32 v9, v30, v31
	global_store_dwordx2 v19, v[6:7], s[2:3]
	global_store_dwordx2 v19, v[8:9], s[2:3] offset:2048
	v_pk_fma_f32 v[24:25], v[14:15], v[24:25], v[142:143]
	v_pk_fma_f32 v[26:27], v[14:15], v[26:27], v[144:145]
	v_pk_fma_f32 v[28:29], v[14:15], v[28:29], v[146:147]
	v_pk_fma_f32 v[30:31], v[14:15], v[30:31], v[148:149]
	s_add_u32 s2, s2, s31
	s_addc_u32 s3, s3, s29
	global_load_dwordx4 v[142:145], v16, s[8:9]
	global_load_dwordx4 v[146:149], v17, s[8:9]
	s_add_u32 s8, s8, s30
	s_addc_u32 s9, s9, s29
	s_waitcnt vmcnt(20)
	v_cvt_pk_bf16_f32 v6, v24, v25
	v_cvt_pk_bf16_f32 v7, v26, v27
	v_cvt_pk_bf16_f32 v8, v28, v29
	v_cvt_pk_bf16_f32 v9, v30, v31
	global_store_dwordx2 v19, v[6:7], s[2:3]
	global_store_dwordx2 v19, v[8:9], s[2:3] offset:2048
	v_pk_fma_f32 v[24:25], v[14:15], v[24:25], v[154:155]
	v_pk_fma_f32 v[26:27], v[14:15], v[26:27], v[156:157]
	v_pk_fma_f32 v[28:29], v[14:15], v[28:29], v[158:159]
	v_pk_fma_f32 v[30:31], v[14:15], v[30:31], v[160:161]
	s_add_u32 s2, s2, s31
	s_addc_u32 s3, s3, s29
	s_waitcnt vmcnt(18)
	v_cvt_pk_bf16_f32 v6, v24, v25
	v_cvt_pk_bf16_f32 v7, v26, v27
	v_cvt_pk_bf16_f32 v8, v28, v29
	v_cvt_pk_bf16_f32 v9, v30, v31
	global_store_dwordx2 v19, v[6:7], s[2:3]
	global_store_dwordx2 v19, v[8:9], s[2:3] offset:2048
	v_pk_fma_f32 v[24:25], v[14:15], v[24:25], v[166:167]
	v_pk_fma_f32 v[26:27], v[14:15], v[26:27], v[168:169]
	v_pk_fma_f32 v[28:29], v[14:15], v[28:29], v[170:171]
	v_pk_fma_f32 v[30:31], v[14:15], v[30:31], v[172:173]
	s_add_u32 s2, s2, s31
	s_addc_u32 s3, s3, s29
	s_waitcnt vmcnt(16)
	v_cvt_pk_bf16_f32 v6, v24, v25
	v_cvt_pk_bf16_f32 v7, v26, v27
	v_cvt_pk_bf16_f32 v8, v28, v29
	v_cvt_pk_bf16_f32 v9, v30, v31
	global_store_dwordx2 v19, v[6:7], s[2:3]
	global_store_dwordx2 v19, v[8:9], s[2:3] offset:2048
	v_pk_fma_f32 v[24:25], v[14:15], v[24:25], v[36:37]
	v_pk_fma_f32 v[26:27], v[14:15], v[26:27], v[38:39]
	v_pk_fma_f32 v[28:29], v[14:15], v[28:29], v[40:41]
	v_pk_fma_f32 v[30:31], v[14:15], v[30:31], v[42:43]
	s_add_u32 s2, s2, s31
	s_addc_u32 s3, s3, s29
	s_waitcnt vmcnt(14)
	v_cvt_pk_bf16_f32 v6, v24, v25
	v_cvt_pk_bf16_f32 v7, v26, v27
	v_cvt_pk_bf16_f32 v8, v28, v29
	v_cvt_pk_bf16_f32 v9, v30, v31
	global_store_dwordx2 v19, v[6:7], s[2:3]
	global_store_dwordx2 v19, v[8:9], s[2:3] offset:2048
	v_pk_fma_f32 v[24:25], v[14:15], v[24:25], v[52:53]
	v_pk_fma_f32 v[26:27], v[14:15], v[26:27], v[54:55]
	v_pk_fma_f32 v[28:29], v[14:15], v[28:29], v[56:57]
	v_pk_fma_f32 v[30:31], v[14:15], v[30:31], v[58:59]
	s_add_u32 s2, s2, s31
	s_addc_u32 s3, s3, s29
	s_waitcnt vmcnt(12)
	v_cvt_pk_bf16_f32 v6, v24, v25
	v_cvt_pk_bf16_f32 v7, v26, v27
	v_cvt_pk_bf16_f32 v8, v28, v29
	v_cvt_pk_bf16_f32 v9, v30, v31
	global_store_dwordx2 v19, v[6:7], s[2:3]
	global_store_dwordx2 v19, v[8:9], s[2:3] offset:2048
	v_pk_fma_f32 v[24:25], v[14:15], v[24:25], v[130:131]
	v_pk_fma_f32 v[26:27], v[14:15], v[26:27], v[132:133]
	v_pk_fma_f32 v[28:29], v[14:15], v[28:29], v[134:135]
	v_pk_fma_f32 v[30:31], v[14:15], v[30:31], v[136:137]
	s_add_u32 s2, s2, s31
	s_addc_u32 s3, s3, s29
	s_waitcnt vmcnt(10)
	v_cvt_pk_bf16_f32 v6, v24, v25
	v_cvt_pk_bf16_f32 v7, v26, v27
	v_cvt_pk_bf16_f32 v8, v28, v29
	v_cvt_pk_bf16_f32 v9, v30, v31
	global_store_dwordx2 v19, v[6:7], s[2:3]
	global_store_dwordx2 v19, v[8:9], s[2:3] offset:2048
	v_pk_fma_f32 v[24:25], v[14:15], v[24:25], v[142:143]
	v_pk_fma_f32 v[26:27], v[14:15], v[26:27], v[144:145]
	v_pk_fma_f32 v[28:29], v[14:15], v[28:29], v[146:147]
	v_pk_fma_f32 v[30:31], v[14:15], v[30:31], v[148:149]
	s_add_u32 s2, s2, s31
	s_addc_u32 s3, s3, s29
	s_branch .LBB0_104
.Lmys_n3:
	global_load_dwordx4 v[130:133], v16, s[8:9]
	global_load_dwordx4 v[134:137], v17, s[8:9]
	global_load_dwordx4 v[138:141], v18, s[8:9]
	s_add_u32 s8, s8, s30
	s_addc_u32 s9, s9, s29
	global_load_dwordx4 v[142:145], v16, s[8:9]
	global_load_dwordx4 v[146:149], v17, s[8:9]
	global_load_dwordx4 v[150:153], v18, s[8:9]
	s_add_u32 s8, s8, s30
	s_addc_u32 s9, s9, s29
	global_load_dwordx4 v[154:157], v16, s[8:9]
	global_load_dwordx4 v[158:161], v17, s[8:9]
	global_load_dwordx4 v[162:165], v18, s[8:9]
	s_add_u32 s8, s8, s30
	s_addc_u32 s9, s9, s29
	global_load_dwordx4 v[166:169], v16, s[8:9]
	global_load_dwordx4 v[170:173], v17, s[8:9]
	global_load_dwordx4 v[174:177], v18, s[8:9]
	s_add_u32 s8, s8, s30
	s_addc_u32 s9, s9, s29
	global_load_dwordx4 v[36:39], v16, s[8:9]
	global_load_dwordx4 v[40:43], v17, s[8:9]
	global_load_dwordx4 v[44:47], v18, s[8:9]
	s_add_u32 s8, s8, s30
	s_addc_u32 s9, s9, s29
	global_load_dwordx4 v[52:55], v16, s[8:9]
	global_load_dwordx4 v[56:59], v17, s[8:9]
	global_load_dwordx4 v[2:5], v18, s[8:9]
	s_add_u32 s8, s8, s30
	s_addc_u32 s9, s9, s29
	s_waitcnt vmcnt(15)
	v_cvt_pk_bf16_f32 v6, v24, v25
	v_cvt_pk_bf16_f32 v7, v26, v27
	v_cvt_pk_bf16_f32 v8, v28, v29
	v_cvt_pk_bf16_f32 v9, v30, v31
	v_cvt_pk_bf16_f32 v10, v32, v33
	v_cvt_pk_bf16_f32 v11, v34, v35
	global_store_dwordx2 v19, v[6:7], s[2:3]
	global_store_dwordx2 v19, v[8:9], s[2:3] offset:2048
	global_store_dwordx2 v20, v[10:11], s[2:3]
	v_pk_fma_f32 v[24:25], v[14:15], v[24:25], v[130:131]
	v_pk_fma_f32 v[26:27], v[14:15], v[26:27], v[132:133]
	v_pk_fma_f32 v[28:29], v[14:15], v[28:29], v[134:135]
	v_pk_fma_f32 v[30:31], v[14:15], v[30:31], v[136:137]
	v_pk_fma_f32 v[32:33], v[14:15], v[32:33], v[138:139]
	v_pk_fma_f32 v[34:35], v[14:15], v[34:35], v[140:141]
	s_add_u32 s2, s2, s31
	s_addc_u32 s3, s3, s29
	global_load_dwordx4 v[130:133], v16, s[8:9]
	global_load_dwordx4 v[134:137], v17, s[8:9]
	global_load_dwordx4 v[138:141], v18, s[8:9]
	s_add_u32 s8, s8, s30
	s_addc_u32 s9, s9, s29
	s_waitcnt vmcnt(18)
	v_cvt_pk_bf16_f32 v6, v24, v25
	v_cvt_pk_bf16_f32 v7, v26, v27
	v_cvt_pk_bf16_f32 v8, v28, v29
	v_cvt_pk_bf16_f32 v9, v30, v31
	v_cvt_pk_bf16_f32 v10, v32, v33
	v_cvt_pk_bf16_f32 v11, v34, v35
	global_store_dwordx2 v19, v[6:7], s[2:3]
	global_store_dwordx2 v19, v[8:9], s[2:3] offset:2048
	global_store_dwordx2 v20, v[10:11], s[2:3]
	v_pk_fma_f32 v[24:25], v[14:15], v[24:25], v[142:143]
	v_pk_fma_f32 v[26:27], v[14:15], v[26:27], v[144:145]
	v_pk_fma_f32 v[28:29], v[14:15], v[28:29], v[146:147]
	v_pk_fma_f32 v[30:31], v[14:15], v[30:31], v[148:149]
	v_pk_fma_f32 v[32:33], v[14:15], v[32:33], v[150:151]
	v_pk_fma_f32 v[34:35], v[14:15], v[34:35], v[152:153]
	s_add_u32 s2, s2, s31
	s_addc_u32 s3, s3, s29
	global_load_dwordx4 v[142:145], v16, s[8:9]
	global_load_dwordx4 v[146:149], v17, s[8:9]
	global_load_dwordx4 v[150:153], v18, s[8:9]
	s_add_u32 s8, s8, s30
	s_addc_u32 s9, s9, s29
	s_waitcnt vmcnt(21)
	v_cvt_pk_bf16_f32 v6, v24, v25
	v_cvt_pk_bf16_f32 v7, v26, v27
	v_cvt_pk_bf16_f32 v8, v28, v29
	v_cvt_pk_bf16_f32 v9, v30, v31
	v_cvt_pk_bf16_f32 v10, v32, v33
	v_cvt_pk_bf16_f32 v11, v34, v35
	global_store_dwordx2 v19, v[6:7], s[2:3]
	global_store_dwordx2 v19, v[8:9], s[2:3] offset:2048
	global_store_dwordx2 v20, v[10:11], s[2:3]
	v_pk_fma_f32 v[24:25], v[14:15], v[24:25], v[154:155]
	v_pk_fma_f32 v[26:27], v[14:15], v[26:27], v[156:157]
	v_pk_fma_f32 v[28:29], v[14:15], v[28:29], v[158:159]
	v_pk_fma_f32 v[30:31], v[14:15], v[30:31], v[160:161]
	v_pk_fma_f32 v[32:33], v[14:15], v[32:33], v[162:163]
	v_pk_fma_f32 v[34:35], v[14:15], v[34:35], v[164:165]
	s_add_u32 s2, s2, s31
	s_addc_u32 s3, s3, s29
	global_load_dwordx4 v[154:157], v16, s[8:9]
	global_load_dwordx4 v[158:161], v17, s[8:9]
	global_load_dwordx4 v[162:165], v18, s[8:9]
	s_add_u32 s8, s8, s30
	s_addc_u32 s9, s9, s29
	s_waitcnt vmcnt(24)
	v_cvt_pk_bf16_f32 v6, v24, v25
	v_cvt_pk_bf16_f32 v7, v26, v27
	v_cvt_pk_bf16_f32 v8, v28, v29
	v_cvt_pk_bf16_f32 v9, v30, v31
	v_cvt_pk_bf16_f32 v10, v32, v33
	v_cvt_pk_bf16_f32 v11, v34, v35
	global_store_dwordx2 v19, v[6:7], s[2:3]
	global_store_dwordx2 v19, v[8:9], s[2:3] offset:2048
	global_store_dwordx2 v20, v[10:11], s[2:3]
	v_pk_fma_f32 v[24:25], v[14:15], v[24:25], v[166:167]
	v_pk_fma_f32 v[26:27], v[14:15], v[26:27], v[168:169]
	v_pk_fma_f32 v[28:29], v[14:15], v[28:29], v[170:171]
	v_pk_fma_f32 v[30:31], v[14:15], v[30:31], v[172:173]
	v_pk_fma_f32 v[32:33], v[14:15], v[32:33], v[174:175]
	v_pk_fma_f32 v[34:35], v[14:15], v[34:35], v[176:177]
	s_add_u32 s2, s2, s31
	s_addc_u32 s3, s3, s29
	global_load_dwordx4 v[166:169], v16, s[8:9]
	global_load_dwordx4 v[170:173], v17, s[8:9]
	global_load_dwordx4 v[174:177], v18, s[8:9]
	s_add_u32 s8, s8, s30
	s_addc_u32 s9, s9, s29
	s_waitcnt vmcnt(27)
	v_cvt_pk_bf16_f32 v6, v24, v25
	v_cvt_pk_bf16_f32 v7, v26, v27
	v_cvt_pk_bf16_f32 v8, v28, v29
	v_cvt_pk_bf16_f32 v9, v30, v31
	v_cvt_pk_bf16_f32 v10, v32, v33
	v_cvt_pk_bf16_f32 v11, v34, v35
	global_store_dwordx2 v19, v[6:7], s[2:3]
	global_store_dwordx2 v19, v[8:9], s[2:3] offset:2048
	global_store_dwordx2 v20, v[10:11], s[2:3]
	v_pk_fma_f32 v[24:25], v[14:15], v[24:25], v[36:37]
	v_pk_fma_f32 v[26:27], v[14:15], v[26:27], v[38:39]
	v_pk_fma_f32 v[28:29], v[14:15], v[28:29], v[40:41]
	v_pk_fma_f32 v[30:31], v[14:15], v[30:31], v[42:43]
	v_pk_fma_f32 v[32:33], v[14:15], v[32:33], v[44:45]
	v_pk_fma_f32 v[34:35], v[14:15], v[34:35], v[46:47]
	s_add_u32 s2, s2, s31
	s_addc_u32 s3, s3, s29
	global_load_dwordx4 v[36:39], v16, s[8:9]
	global_load_dwordx4 v[40:43], v17, s[8:9]
	global_load_dwordx4 v[44:47], v18, s[8:9]
	s_add_u32 s8, s8, s30
	s_addc_u32 s9, s9, s29
	s_waitcnt vmcnt(30)
	v_cvt_pk_bf16_f32 v6, v24, v25
	v_cvt_pk_bf16_f32 v7, v26, v27
	v_cvt_pk_bf16_f32 v8, v28, v29
	v_cvt_pk_bf16_f32 v9, v30, v31
	v_cvt_pk_bf16_f32 v10, v32, v33
	v_cvt_pk_bf16_f32 v11, v34, v35
	global_store_dwordx2 v19, v[6:7], s[2:3]
	global_store_dwordx2 v19, v[8:9], s[2:3] offset:2048
	global_store_dwordx2 v20, v[10:11], s[2:3]
	v_pk_fma_f32 v[24:25], v[14:15], v[24:25], v[52:53]
	v_pk_fma_f32 v[26:27], v[14:15], v[26:27], v[54:55]
	v_pk_fma_f32 v[28:29], v[14:15], v[28:29], v[56:57]
	v_pk_fma_f32 v[30:31], v[14:15], v[30:31], v[58:59]
	v_pk_fma_f32 v[32:33], v[14:15], v[32:33], v[2:3]
	v_pk_fma_f32 v[34:35], v[14:15], v[34:35], v[4:5]
	s_add_u32 s2, s2, s31
	s_addc_u32 s3, s3, s29
	global_load_dwordx4 v[52:55], v16, s[8:9]
	global_load_dwordx4 v[56:59], v17, s[8:9]
	global_load_dwordx4 v[2:5], v18, s[8:9]
	s_add_u32 s8, s8, s30
	s_addc_u32 s9, s9, s29
	s_waitcnt vmcnt(30)
	v_cvt_pk_bf16_f32 v6, v24, v25
	v_cvt_pk_bf16_f32 v7, v26, v27
	v_cvt_pk_bf16_f32 v8, v28, v29
	v_cvt_pk_bf16_f32 v9, v30, v31
	v_cvt_pk_bf16_f32 v10, v32, v33
	v_cvt_pk_bf16_f32 v11, v34, v35
	global_store_dwordx2 v19, v[6:7], s[2:3]
	global_store_dwordx2 v19, v[8:9], s[2:3] offset:2048
	global_store_dwordx2 v20, v[10:11], s[2:3]
	v_pk_fma_f32 v[24:25], v[14:15], v[24:25], v[130:131]
	v_pk_fma_f32 v[26:27], v[14:15], v[26:27], v[132:133]
	v_pk_fma_f32 v[28:29], v[14:15], v[28:29], v[134:135]
	v_pk_fma_f32 v[30:31], v[14:15], v[30:31], v[136:137]
	v_pk_fma_f32 v[32:33], v[14:15], v[32:33], v[138:139]
	v_pk_fma_f32 v[34:35], v[14:15], v[34:35], v[140:141]
	s_add_u32 s2, s2, s31
	s_addc_u32 s3, s3, s29
	global_load_dwordx4 v[130:133], v16, s[8:9]
	global_load_dwordx4 v[134:137], v17, s[8:9]
	global_load_dwordx4 v[138:141], v18, s[8:9]
	s_add_u32 s8, s8, s30
	s_addc_u32 s9, s9, s29
	s_waitcnt vmcnt(30)
	v_cvt_pk_bf16_f32 v6, v24, v25
	v_cvt_pk_bf16_f32 v7, v26, v27
	v_cvt_pk_bf16_f32 v8, v28, v29
	v_cvt_pk_bf16_f32 v9, v30, v31
	v_cvt_pk_bf16_f32 v10, v32, v33
	v_cvt_pk_bf16_f32 v11, v34, v35
	global_store_dwordx2 v19, v[6:7], s[2:3]
	global_store_dwordx2 v19, v[8:9], s[2:3] offset:2048
	global_store_dwordx2 v20, v[10:11], s[2:3]
	v_pk_fma_f32 v[24:25], v[14:15], v[24:25], v[142:143]
	v_pk_fma_f32 v[26:27], v[14:15], v[26:27], v[144:145]
	v_pk_fma_f32 v[28:29], v[14:15], v[28:29], v[146:147]
	v_pk_fma_f32 v[30:31], v[14:15], v[30:31], v[148:149]
	v_pk_fma_f32 v[32:33], v[14:15], v[32:33], v[150:151]
	v_pk_fma_f32 v[34:35], v[14:15], v[34:35], v[152:153]
	s_add_u32 s2, s2, s31
	s_addc_u32 s3, s3, s29
	global_load_dwordx4 v[142:145], v16, s[8:9]
	global_load_dwordx4 v[146:149], v17, s[8:9]
	global_load_dwordx4 v[150:153], v18, s[8:9]
	s_add_u32 s8, s8, s30
	s_addc_u32 s9, s9, s29
	s_waitcnt vmcnt(30)
	v_cvt_pk_bf16_f32 v6, v24, v25
	v_cvt_pk_bf16_f32 v7, v26, v27
	v_cvt_pk_bf16_f32 v8, v28, v29
	v_cvt_pk_bf16_f32 v9, v30, v31
	v_cvt_pk_bf16_f32 v10, v32, v33
	v_cvt_pk_bf16_f32 v11, v34, v35
	global_store_dwordx2 v19, v[6:7], s[2:3]
	global_store_dwordx2 v19, v[8:9], s[2:3] offset:2048
	global_store_dwordx2 v20, v[10:11], s[2:3]
	v_pk_fma_f32 v[24:25], v[14:15], v[24:25], v[154:155]
	v_pk_fma_f32 v[26:27], v[14:15], v[26:27], v[156:157]
	v_pk_fma_f32 v[28:29], v[14:15], v[28:29], v[158:159]
	v_pk_fma_f32 v[30:31], v[14:15], v[30:31], v[160:161]
	v_pk_fma_f32 v[32:33], v[14:15], v[32:33], v[162:163]
	v_pk_fma_f32 v[34:35], v[14:15], v[34:35], v[164:165]
	s_add_u32 s2, s2, s31
	s_addc_u32 s3, s3, s29
	global_load_dwordx4 v[154:157], v16, s[8:9]
	global_load_dwordx4 v[158:161], v17, s[8:9]
	global_load_dwordx4 v[162:165], v18, s[8:9]
	s_add_u32 s8, s8, s30
	s_addc_u32 s9, s9, s29
	s_waitcnt vmcnt(30)
	v_cvt_pk_bf16_f32 v6, v24, v25
	v_cvt_pk_bf16_f32 v7, v26, v27
	v_cvt_pk_bf16_f32 v8, v28, v29
	v_cvt_pk_bf16_f32 v9, v30, v31
	v_cvt_pk_bf16_f32 v10, v32, v33
	v_cvt_pk_bf16_f32 v11, v34, v35
	global_store_dwordx2 v19, v[6:7], s[2:3]
	global_store_dwordx2 v19, v[8:9], s[2:3] offset:2048
	global_store_dwordx2 v20, v[10:11], s[2:3]
	v_pk_fma_f32 v[24:25], v[14:15], v[24:25], v[166:167]
	v_pk_fma_f32 v[26:27], v[14:15], v[26:27], v[168:169]
	v_pk_fma_f32 v[28:29], v[14:15], v[28:29], v[170:171]
	v_pk_fma_f32 v[30:31], v[14:15], v[30:31], v[172:173]
	v_pk_fma_f32 v[32:33], v[14:15], v[32:33], v[174:175]
	v_pk_fma_f32 v[34:35], v[14:15], v[34:35], v[176:177]
	s_add_u32 s2, s2, s31
	s_addc_u32 s3, s3, s29
	global_load_dwordx4 v[166:169], v16, s[8:9]
	global_load_dwordx4 v[170:173], v17, s[8:9]
	global_load_dwordx4 v[174:177], v18, s[8:9]
	s_add_u32 s8, s8, s30
	s_addc_u32 s9, s9, s29
	s_waitcnt vmcnt(30)
	v_cvt_pk_bf16_f32 v6, v24, v25
	v_cvt_pk_bf16_f32 v7, v26, v27
	v_cvt_pk_bf16_f32 v8, v28, v29
	v_cvt_pk_bf16_f32 v9, v30, v31
	v_cvt_pk_bf16_f32 v10, v32, v33
	v_cvt_pk_bf16_f32 v11, v34, v35
	global_store_dwordx2 v19, v[6:7], s[2:3]
	global_store_dwordx2 v19, v[8:9], s[2:3] offset:2048
	global_store_dwordx2 v20, v[10:11], s[2:3]
	v_pk_fma_f32 v[24:25], v[14:15], v[24:25], v[36:37]
	v_pk_fma_f32 v[26:27], v[14:15], v[26:27], v[38:39]
	v_pk_fma_f32 v[28:29], v[14:15], v[28:29], v[40:41]
	v_pk_fma_f32 v[30:31], v[14:15], v[30:31], v[42:43]
	v_pk_fma_f32 v[32:33], v[14:15], v[32:33], v[44:45]
	v_pk_fma_f32 v[34:35], v[14:15], v[34:35], v[46:47]
	s_add_u32 s2, s2, s31
	s_addc_u32 s3, s3, s29
	global_load_dwordx4 v[36:39], v16, s[8:9]
	global_load_dwordx4 v[40:43], v17, s[8:9]
	global_load_dwordx4 v[44:47], v18, s[8:9]
	s_add_u32 s8, s8, s30
	s_addc_u32 s9, s9, s29
	s_waitcnt vmcnt(30)
	v_cvt_pk_bf16_f32 v6, v24, v25
	v_cvt_pk_bf16_f32 v7, v26, v27
	v_cvt_pk_bf16_f32 v8, v28, v29
	v_cvt_pk_bf16_f32 v9, v30, v31
	v_cvt_pk_bf16_f32 v10, v32, v33
	v_cvt_pk_bf16_f32 v11, v34, v35
	global_store_dwordx2 v19, v[6:7], s[2:3]
	global_store_dwordx2 v19, v[8:9], s[2:3] offset:2048
	global_store_dwordx2 v20, v[10:11], s[2:3]
	v_pk_fma_f32 v[24:25], v[14:15], v[24:25], v[52:53]
	v_pk_fma_f32 v[26:27], v[14:15], v[26:27], v[54:55]
	v_pk_fma_f32 v[28:29], v[14:15], v[28:29], v[56:57]
	v_pk_fma_f32 v[30:31], v[14:15], v[30:31], v[58:59]
	v_pk_fma_f32 v[32:33], v[14:15], v[32:33], v[2:3]
	v_pk_fma_f32 v[34:35], v[14:15], v[34:35], v[4:5]
	s_add_u32 s2, s2, s31
	s_addc_u32 s3, s3, s29
	global_load_dwordx4 v[52:55], v16, s[8:9]
	global_load_dwordx4 v[56:59], v17, s[8:9]
	global_load_dwordx4 v[2:5], v18, s[8:9]
	s_add_u32 s8, s8, s30
	s_addc_u32 s9, s9, s29
	s_waitcnt vmcnt(30)
	v_cvt_pk_bf16_f32 v6, v24, v25
	v_cvt_pk_bf16_f32 v7, v26, v27
	v_cvt_pk_bf16_f32 v8, v28, v29
	v_cvt_pk_bf16_f32 v9, v30, v31
	v_cvt_pk_bf16_f32 v10, v32, v33
	v_cvt_pk_bf16_f32 v11, v34, v35
	global_store_dwordx2 v19, v[6:7], s[2:3]
	global_store_dwordx2 v19, v[8:9], s[2:3] offset:2048
	global_store_dwordx2 v20, v[10:11], s[2:3]
	v_pk_fma_f32 v[24:25], v[14:15], v[24:25], v[130:131]
	v_pk_fma_f32 v[26:27], v[14:15], v[26:27], v[132:133]
	v_pk_fma_f32 v[28:29], v[14:15], v[28:29], v[134:135]
	v_pk_fma_f32 v[30:31], v[14:15], v[30:31], v[136:137]
	v_pk_fma_f32 v[32:33], v[14:15], v[32:33], v[138:139]
	v_pk_fma_f32 v[34:35], v[14:15], v[34:35], v[140:141]
	s_add_u32 s2, s2, s31
	s_addc_u32 s3, s3, s29
	global_load_dwordx4 v[130:133], v16, s[8:9]
	global_load_dwordx4 v[134:137], v17, s[8:9]
	global_load_dwordx4 v[138:141], v18, s[8:9]
	s_add_u32 s8, s8, s30
	s_addc_u32 s9, s9, s29
	s_waitcnt vmcnt(30)
	v_cvt_pk_bf16_f32 v6, v24, v25
	v_cvt_pk_bf16_f32 v7, v26, v27
	v_cvt_pk_bf16_f32 v8, v28, v29
	v_cvt_pk_bf16_f32 v9, v30, v31
	v_cvt_pk_bf16_f32 v10, v32, v33
	v_cvt_pk_bf16_f32 v11, v34, v35
	global_store_dwordx2 v19, v[6:7], s[2:3]
	global_store_dwordx2 v19, v[8:9], s[2:3] offset:2048
	global_store_dwordx2 v20, v[10:11], s[2:3]
	v_pk_fma_f32 v[24:25], v[14:15], v[24:25], v[142:143]
	v_pk_fma_f32 v[26:27], v[14:15], v[26:27], v[144:145]
	v_pk_fma_f32 v[28:29], v[14:15], v[28:29], v[146:147]
	v_pk_fma_f32 v[30:31], v[14:15], v[30:31], v[148:149]
	v_pk_fma_f32 v[32:33], v[14:15], v[32:33], v[150:151]
	v_pk_fma_f32 v[34:35], v[14:15], v[34:35], v[152:153]
	s_add_u32 s2, s2, s31
	s_addc_u32 s3, s3, s29
	global_load_dwordx4 v[142:145], v16, s[8:9]
	global_load_dwordx4 v[146:149], v17, s[8:9]
	global_load_dwordx4 v[150:153], v18, s[8:9]
	s_add_u32 s8, s8, s30
	s_addc_u32 s9, s9, s29
	s_waitcnt vmcnt(30)
	v_cvt_pk_bf16_f32 v6, v24, v25
	v_cvt_pk_bf16_f32 v7, v26, v27
	v_cvt_pk_bf16_f32 v8, v28, v29
	v_cvt_pk_bf16_f32 v9, v30, v31
	v_cvt_pk_bf16_f32 v10, v32, v33
	v_cvt_pk_bf16_f32 v11, v34, v35
	global_store_dwordx2 v19, v[6:7], s[2:3]
	global_store_dwordx2 v19, v[8:9], s[2:3] offset:2048
	global_store_dwordx2 v20, v[10:11], s[2:3]
	v_pk_fma_f32 v[24:25], v[14:15], v[24:25], v[154:155]
	v_pk_fma_f32 v[26:27], v[14:15], v[26:27], v[156:157]
	v_pk_fma_f32 v[28:29], v[14:15], v[28:29], v[158:159]
	v_pk_fma_f32 v[30:31], v[14:15], v[30:31], v[160:161]
	v_pk_fma_f32 v[32:33], v[14:15], v[32:33], v[162:163]
	v_pk_fma_f32 v[34:35], v[14:15], v[34:35], v[164:165]
	s_add_u32 s2, s2, s31
	s_addc_u32 s3, s3, s29
	global_load_dwordx4 v[154:157], v16, s[8:9]
	global_load_dwordx4 v[158:161], v17, s[8:9]
	global_load_dwordx4 v[162:165], v18, s[8:9]
	s_add_u32 s8, s8, s30
	s_addc_u32 s9, s9, s29
	s_waitcnt vmcnt(30)
	v_cvt_pk_bf16_f32 v6, v24, v25
	v_cvt_pk_bf16_f32 v7, v26, v27
	v_cvt_pk_bf16_f32 v8, v28, v29
	v_cvt_pk_bf16_f32 v9, v30, v31
	v_cvt_pk_bf16_f32 v10, v32, v33
	v_cvt_pk_bf16_f32 v11, v34, v35
	global_store_dwordx2 v19, v[6:7], s[2:3]
	global_store_dwordx2 v19, v[8:9], s[2:3] offset:2048
	global_store_dwordx2 v20, v[10:11], s[2:3]
	v_pk_fma_f32 v[24:25], v[14:15], v[24:25], v[166:167]
	v_pk_fma_f32 v[26:27], v[14:15], v[26:27], v[168:169]
	v_pk_fma_f32 v[28:29], v[14:15], v[28:29], v[170:171]
	v_pk_fma_f32 v[30:31], v[14:15], v[30:31], v[172:173]
	v_pk_fma_f32 v[32:33], v[14:15], v[32:33], v[174:175]
	v_pk_fma_f32 v[34:35], v[14:15], v[34:35], v[176:177]
	s_add_u32 s2, s2, s31
	s_addc_u32 s3, s3, s29
	global_load_dwordx4 v[166:169], v16, s[8:9]
	global_load_dwordx4 v[170:173], v17, s[8:9]
	global_load_dwordx4 v[174:177], v18, s[8:9]
	s_add_u32 s8, s8, s30
	s_addc_u32 s9, s9, s29
	s_waitcnt vmcnt(30)
	v_cvt_pk_bf16_f32 v6, v24, v25
	v_cvt_pk_bf16_f32 v7, v26, v27
	v_cvt_pk_bf16_f32 v8, v28, v29
	v_cvt_pk_bf16_f32 v9, v30, v31
	v_cvt_pk_bf16_f32 v10, v32, v33
	v_cvt_pk_bf16_f32 v11, v34, v35
	global_store_dwordx2 v19, v[6:7], s[2:3]
	global_store_dwordx2 v19, v[8:9], s[2:3] offset:2048
	global_store_dwordx2 v20, v[10:11], s[2:3]
	v_pk_fma_f32 v[24:25], v[14:15], v[24:25], v[36:37]
	v_pk_fma_f32 v[26:27], v[14:15], v[26:27], v[38:39]
	v_pk_fma_f32 v[28:29], v[14:15], v[28:29], v[40:41]
	v_pk_fma_f32 v[30:31], v[14:15], v[30:31], v[42:43]
	v_pk_fma_f32 v[32:33], v[14:15], v[32:33], v[44:45]
	v_pk_fma_f32 v[34:35], v[14:15], v[34:35], v[46:47]
	s_add_u32 s2, s2, s31
	s_addc_u32 s3, s3, s29
	global_load_dwordx4 v[36:39], v16, s[8:9]
	global_load_dwordx4 v[40:43], v17, s[8:9]
	global_load_dwordx4 v[44:47], v18, s[8:9]
	s_add_u32 s8, s8, s30
	s_addc_u32 s9, s9, s29
	s_waitcnt vmcnt(30)
	v_cvt_pk_bf16_f32 v6, v24, v25
	v_cvt_pk_bf16_f32 v7, v26, v27
	v_cvt_pk_bf16_f32 v8, v28, v29
	v_cvt_pk_bf16_f32 v9, v30, v31
	v_cvt_pk_bf16_f32 v10, v32, v33
	v_cvt_pk_bf16_f32 v11, v34, v35
	global_store_dwordx2 v19, v[6:7], s[2:3]
	global_store_dwordx2 v19, v[8:9], s[2:3] offset:2048
	global_store_dwordx2 v20, v[10:11], s[2:3]
	v_pk_fma_f32 v[24:25], v[14:15], v[24:25], v[52:53]
	v_pk_fma_f32 v[26:27], v[14:15], v[26:27], v[54:55]
	v_pk_fma_f32 v[28:29], v[14:15], v[28:29], v[56:57]
	v_pk_fma_f32 v[30:31], v[14:15], v[30:31], v[58:59]
	v_pk_fma_f32 v[32:33], v[14:15], v[32:33], v[2:3]
	v_pk_fma_f32 v[34:35], v[14:15], v[34:35], v[4:5]
	s_add_u32 s2, s2, s31
	s_addc_u32 s3, s3, s29
	global_load_dwordx4 v[52:55], v16, s[8:9]
	global_load_dwordx4 v[56:59], v17, s[8:9]
	global_load_dwordx4 v[2:5], v18, s[8:9]
	s_add_u32 s8, s8, s30
	s_addc_u32 s9, s9, s29
	s_waitcnt vmcnt(30)
	v_cvt_pk_bf16_f32 v6, v24, v25
	v_cvt_pk_bf16_f32 v7, v26, v27
	v_cvt_pk_bf16_f32 v8, v28, v29
	v_cvt_pk_bf16_f32 v9, v30, v31
	v_cvt_pk_bf16_f32 v10, v32, v33
	v_cvt_pk_bf16_f32 v11, v34, v35
	global_store_dwordx2 v19, v[6:7], s[2:3]
	global_store_dwordx2 v19, v[8:9], s[2:3] offset:2048
	global_store_dwordx2 v20, v[10:11], s[2:3]
	v_pk_fma_f32 v[24:25], v[14:15], v[24:25], v[130:131]
	v_pk_fma_f32 v[26:27], v[14:15], v[26:27], v[132:133]
	v_pk_fma_f32 v[28:29], v[14:15], v[28:29], v[134:135]
	v_pk_fma_f32 v[30:31], v[14:15], v[30:31], v[136:137]
	v_pk_fma_f32 v[32:33], v[14:15], v[32:33], v[138:139]
	v_pk_fma_f32 v[34:35], v[14:15], v[34:35], v[140:141]
	s_add_u32 s2, s2, s31
	s_addc_u32 s3, s3, s29
	global_load_dwordx4 v[130:133], v16, s[8:9]
	global_load_dwordx4 v[134:137], v17, s[8:9]
	global_load_dwordx4 v[138:141], v18, s[8:9]
	s_add_u32 s8, s8, s30
	s_addc_u32 s9, s9, s29
	s_waitcnt vmcnt(30)
	v_cvt_pk_bf16_f32 v6, v24, v25
	v_cvt_pk_bf16_f32 v7, v26, v27
	v_cvt_pk_bf16_f32 v8, v28, v29
	v_cvt_pk_bf16_f32 v9, v30, v31
	v_cvt_pk_bf16_f32 v10, v32, v33
	v_cvt_pk_bf16_f32 v11, v34, v35
	global_store_dwordx2 v19, v[6:7], s[2:3]
	global_store_dwordx2 v19, v[8:9], s[2:3] offset:2048
	global_store_dwordx2 v20, v[10:11], s[2:3]
	v_pk_fma_f32 v[24:25], v[14:15], v[24:25], v[142:143]
	v_pk_fma_f32 v[26:27], v[14:15], v[26:27], v[144:145]
	v_pk_fma_f32 v[28:29], v[14:15], v[28:29], v[146:147]
	v_pk_fma_f32 v[30:31], v[14:15], v[30:31], v[148:149]
	v_pk_fma_f32 v[32:33], v[14:15], v[32:33], v[150:151]
	v_pk_fma_f32 v[34:35], v[14:15], v[34:35], v[152:153]
	s_add_u32 s2, s2, s31
	s_addc_u32 s3, s3, s29
	global_load_dwordx4 v[142:145], v16, s[8:9]
	global_load_dwordx4 v[146:149], v17, s[8:9]
	global_load_dwordx4 v[150:153], v18, s[8:9]
	s_add_u32 s8, s8, s30
	s_addc_u32 s9, s9, s29
	s_waitcnt vmcnt(30)
	v_cvt_pk_bf16_f32 v6, v24, v25
	v_cvt_pk_bf16_f32 v7, v26, v27
	v_cvt_pk_bf16_f32 v8, v28, v29
	v_cvt_pk_bf16_f32 v9, v30, v31
	v_cvt_pk_bf16_f32 v10, v32, v33
	v_cvt_pk_bf16_f32 v11, v34, v35
	global_store_dwordx2 v19, v[6:7], s[2:3]
	global_store_dwordx2 v19, v[8:9], s[2:3] offset:2048
	global_store_dwordx2 v20, v[10:11], s[2:3]
	v_pk_fma_f32 v[24:25], v[14:15], v[24:25], v[154:155]
	v_pk_fma_f32 v[26:27], v[14:15], v[26:27], v[156:157]
	v_pk_fma_f32 v[28:29], v[14:15], v[28:29], v[158:159]
	v_pk_fma_f32 v[30:31], v[14:15], v[30:31], v[160:161]
	v_pk_fma_f32 v[32:33], v[14:15], v[32:33], v[162:163]
	v_pk_fma_f32 v[34:35], v[14:15], v[34:35], v[164:165]
	s_add_u32 s2, s2, s31
	s_addc_u32 s3, s3, s29
	global_load_dwordx4 v[154:157], v16, s[8:9]
	global_load_dwordx4 v[158:161], v17, s[8:9]
	global_load_dwordx4 v[162:165], v18, s[8:9]
	s_add_u32 s8, s8, s30
	s_addc_u32 s9, s9, s29
	s_waitcnt vmcnt(30)
	v_cvt_pk_bf16_f32 v6, v24, v25
	v_cvt_pk_bf16_f32 v7, v26, v27
	v_cvt_pk_bf16_f32 v8, v28, v29
	v_cvt_pk_bf16_f32 v9, v30, v31
	v_cvt_pk_bf16_f32 v10, v32, v33
	v_cvt_pk_bf16_f32 v11, v34, v35
	global_store_dwordx2 v19, v[6:7], s[2:3]
	global_store_dwordx2 v19, v[8:9], s[2:3] offset:2048
	global_store_dwordx2 v20, v[10:11], s[2:3]
	v_pk_fma_f32 v[24:25], v[14:15], v[24:25], v[166:167]
	v_pk_fma_f32 v[26:27], v[14:15], v[26:27], v[168:169]
	v_pk_fma_f32 v[28:29], v[14:15], v[28:29], v[170:171]
	v_pk_fma_f32 v[30:31], v[14:15], v[30:31], v[172:173]
	v_pk_fma_f32 v[32:33], v[14:15], v[32:33], v[174:175]
	v_pk_fma_f32 v[34:35], v[14:15], v[34:35], v[176:177]
	s_add_u32 s2, s2, s31
	s_addc_u32 s3, s3, s29
	global_load_dwordx4 v[166:169], v16, s[8:9]
	global_load_dwordx4 v[170:173], v17, s[8:9]
	global_load_dwordx4 v[174:177], v18, s[8:9]
	s_add_u32 s8, s8, s30
	s_addc_u32 s9, s9, s29
	s_waitcnt vmcnt(30)
	v_cvt_pk_bf16_f32 v6, v24, v25
	v_cvt_pk_bf16_f32 v7, v26, v27
	v_cvt_pk_bf16_f32 v8, v28, v29
	v_cvt_pk_bf16_f32 v9, v30, v31
	v_cvt_pk_bf16_f32 v10, v32, v33
	v_cvt_pk_bf16_f32 v11, v34, v35
	global_store_dwordx2 v19, v[6:7], s[2:3]
	global_store_dwordx2 v19, v[8:9], s[2:3] offset:2048
	global_store_dwordx2 v20, v[10:11], s[2:3]
	v_pk_fma_f32 v[24:25], v[14:15], v[24:25], v[36:37]
	v_pk_fma_f32 v[26:27], v[14:15], v[26:27], v[38:39]
	v_pk_fma_f32 v[28:29], v[14:15], v[28:29], v[40:41]
	v_pk_fma_f32 v[30:31], v[14:15], v[30:31], v[42:43]
	v_pk_fma_f32 v[32:33], v[14:15], v[32:33], v[44:45]
	v_pk_fma_f32 v[34:35], v[14:15], v[34:35], v[46:47]
	s_add_u32 s2, s2, s31
	s_addc_u32 s3, s3, s29
	global_load_dwordx4 v[36:39], v16, s[8:9]
	global_load_dwordx4 v[40:43], v17, s[8:9]
	global_load_dwordx4 v[44:47], v18, s[8:9]
	s_add_u32 s8, s8, s30
	s_addc_u32 s9, s9, s29
	s_waitcnt vmcnt(30)
	v_cvt_pk_bf16_f32 v6, v24, v25
	v_cvt_pk_bf16_f32 v7, v26, v27
	v_cvt_pk_bf16_f32 v8, v28, v29
	v_cvt_pk_bf16_f32 v9, v30, v31
	v_cvt_pk_bf16_f32 v10, v32, v33
	v_cvt_pk_bf16_f32 v11, v34, v35
	global_store_dwordx2 v19, v[6:7], s[2:3]
	global_store_dwordx2 v19, v[8:9], s[2:3] offset:2048
	global_store_dwordx2 v20, v[10:11], s[2:3]
	v_pk_fma_f32 v[24:25], v[14:15], v[24:25], v[52:53]
	v_pk_fma_f32 v[26:27], v[14:15], v[26:27], v[54:55]
	v_pk_fma_f32 v[28:29], v[14:15], v[28:29], v[56:57]
	v_pk_fma_f32 v[30:31], v[14:15], v[30:31], v[58:59]
	v_pk_fma_f32 v[32:33], v[14:15], v[32:33], v[2:3]
	v_pk_fma_f32 v[34:35], v[14:15], v[34:35], v[4:5]
	s_add_u32 s2, s2, s31
	s_addc_u32 s3, s3, s29
	global_load_dwordx4 v[52:55], v16, s[8:9]
	global_load_dwordx4 v[56:59], v17, s[8:9]
	global_load_dwordx4 v[2:5], v18, s[8:9]
	s_add_u32 s8, s8, s30
	s_addc_u32 s9, s9, s29
	s_waitcnt vmcnt(30)
	v_cvt_pk_bf16_f32 v6, v24, v25
	v_cvt_pk_bf16_f32 v7, v26, v27
	v_cvt_pk_bf16_f32 v8, v28, v29
	v_cvt_pk_bf16_f32 v9, v30, v31
	v_cvt_pk_bf16_f32 v10, v32, v33
	v_cvt_pk_bf16_f32 v11, v34, v35
	global_store_dwordx2 v19, v[6:7], s[2:3]
	global_store_dwordx2 v19, v[8:9], s[2:3] offset:2048
	global_store_dwordx2 v20, v[10:11], s[2:3]
	v_pk_fma_f32 v[24:25], v[14:15], v[24:25], v[130:131]
	v_pk_fma_f32 v[26:27], v[14:15], v[26:27], v[132:133]
	v_pk_fma_f32 v[28:29], v[14:15], v[28:29], v[134:135]
	v_pk_fma_f32 v[30:31], v[14:15], v[30:31], v[136:137]
	v_pk_fma_f32 v[32:33], v[14:15], v[32:33], v[138:139]
	v_pk_fma_f32 v[34:35], v[14:15], v[34:35], v[140:141]
	s_add_u32 s2, s2, s31
	s_addc_u32 s3, s3, s29
	global_load_dwordx4 v[130:133], v16, s[8:9]
	global_load_dwordx4 v[134:137], v17, s[8:9]
	global_load_dwordx4 v[138:141], v18, s[8:9]
	s_add_u32 s8, s8, s30
	s_addc_u32 s9, s9, s29
	s_waitcnt vmcnt(30)
	v_cvt_pk_bf16_f32 v6, v24, v25
	v_cvt_pk_bf16_f32 v7, v26, v27
	v_cvt_pk_bf16_f32 v8, v28, v29
	v_cvt_pk_bf16_f32 v9, v30, v31
	v_cvt_pk_bf16_f32 v10, v32, v33
	v_cvt_pk_bf16_f32 v11, v34, v35
	global_store_dwordx2 v19, v[6:7], s[2:3]
	global_store_dwordx2 v19, v[8:9], s[2:3] offset:2048
	global_store_dwordx2 v20, v[10:11], s[2:3]
	v_pk_fma_f32 v[24:25], v[14:15], v[24:25], v[142:143]
	v_pk_fma_f32 v[26:27], v[14:15], v[26:27], v[144:145]
	v_pk_fma_f32 v[28:29], v[14:15], v[28:29], v[146:147]
	v_pk_fma_f32 v[30:31], v[14:15], v[30:31], v[148:149]
	v_pk_fma_f32 v[32:33], v[14:15], v[32:33], v[150:151]
	v_pk_fma_f32 v[34:35], v[14:15], v[34:35], v[152:153]
	s_add_u32 s2, s2, s31
	s_addc_u32 s3, s3, s29
	global_load_dwordx4 v[142:145], v16, s[8:9]
	global_load_dwordx4 v[146:149], v17, s[8:9]
	global_load_dwordx4 v[150:153], v18, s[8:9]
	s_add_u32 s8, s8, s30
	s_addc_u32 s9, s9, s29
	s_waitcnt vmcnt(30)
	v_cvt_pk_bf16_f32 v6, v24, v25
	v_cvt_pk_bf16_f32 v7, v26, v27
	v_cvt_pk_bf16_f32 v8, v28, v29
	v_cvt_pk_bf16_f32 v9, v30, v31
	v_cvt_pk_bf16_f32 v10, v32, v33
	v_cvt_pk_bf16_f32 v11, v34, v35
	global_store_dwordx2 v19, v[6:7], s[2:3]
	global_store_dwordx2 v19, v[8:9], s[2:3] offset:2048
	global_store_dwordx2 v20, v[10:11], s[2:3]
	v_pk_fma_f32 v[24:25], v[14:15], v[24:25], v[154:155]
	v_pk_fma_f32 v[26:27], v[14:15], v[26:27], v[156:157]
	v_pk_fma_f32 v[28:29], v[14:15], v[28:29], v[158:159]
	v_pk_fma_f32 v[30:31], v[14:15], v[30:31], v[160:161]
	v_pk_fma_f32 v[32:33], v[14:15], v[32:33], v[162:163]
	v_pk_fma_f32 v[34:35], v[14:15], v[34:35], v[164:165]
	s_add_u32 s2, s2, s31
	s_addc_u32 s3, s3, s29
	s_waitcnt vmcnt(27)
	v_cvt_pk_bf16_f32 v6, v24, v25
	v_cvt_pk_bf16_f32 v7, v26, v27
	v_cvt_pk_bf16_f32 v8, v28, v29
	v_cvt_pk_bf16_f32 v9, v30, v31
	v_cvt_pk_bf16_f32 v10, v32, v33
	v_cvt_pk_bf16_f32 v11, v34, v35
	global_store_dwordx2 v19, v[6:7], s[2:3]
	global_store_dwordx2 v19, v[8:9], s[2:3] offset:2048
	global_store_dwordx2 v20, v[10:11], s[2:3]
	v_pk_fma_f32 v[24:25], v[14:15], v[24:25], v[166:167]
	v_pk_fma_f32 v[26:27], v[14:15], v[26:27], v[168:169]
	v_pk_fma_f32 v[28:29], v[14:15], v[28:29], v[170:171]
	v_pk_fma_f32 v[30:31], v[14:15], v[30:31], v[172:173]
	v_pk_fma_f32 v[32:33], v[14:15], v[32:33], v[174:175]
	v_pk_fma_f32 v[34:35], v[14:15], v[34:35], v[176:177]
	s_add_u32 s2, s2, s31
	s_addc_u32 s3, s3, s29
	s_waitcnt vmcnt(24)
	v_cvt_pk_bf16_f32 v6, v24, v25
	v_cvt_pk_bf16_f32 v7, v26, v27
	v_cvt_pk_bf16_f32 v8, v28, v29
	v_cvt_pk_bf16_f32 v9, v30, v31
	v_cvt_pk_bf16_f32 v10, v32, v33
	v_cvt_pk_bf16_f32 v11, v34, v35
	global_store_dwordx2 v19, v[6:7], s[2:3]
	global_store_dwordx2 v19, v[8:9], s[2:3] offset:2048
	global_store_dwordx2 v20, v[10:11], s[2:3]
	v_pk_fma_f32 v[24:25], v[14:15], v[24:25], v[36:37]
	v_pk_fma_f32 v[26:27], v[14:15], v[26:27], v[38:39]
	v_pk_fma_f32 v[28:29], v[14:15], v[28:29], v[40:41]
	v_pk_fma_f32 v[30:31], v[14:15], v[30:31], v[42:43]
	v_pk_fma_f32 v[32:33], v[14:15], v[32:33], v[44:45]
	v_pk_fma_f32 v[34:35], v[14:15], v[34:35], v[46:47]
	s_add_u32 s2, s2, s31
	s_addc_u32 s3, s3, s29
	s_waitcnt vmcnt(21)
	v_cvt_pk_bf16_f32 v6, v24, v25
	v_cvt_pk_bf16_f32 v7, v26, v27
	v_cvt_pk_bf16_f32 v8, v28, v29
	v_cvt_pk_bf16_f32 v9, v30, v31
	v_cvt_pk_bf16_f32 v10, v32, v33
	v_cvt_pk_bf16_f32 v11, v34, v35
	global_store_dwordx2 v19, v[6:7], s[2:3]
	global_store_dwordx2 v19, v[8:9], s[2:3] offset:2048
	global_store_dwordx2 v20, v[10:11], s[2:3]
	v_pk_fma_f32 v[24:25], v[14:15], v[24:25], v[52:53]
	v_pk_fma_f32 v[26:27], v[14:15], v[26:27], v[54:55]
	v_pk_fma_f32 v[28:29], v[14:15], v[28:29], v[56:57]
	v_pk_fma_f32 v[30:31], v[14:15], v[30:31], v[58:59]
	v_pk_fma_f32 v[32:33], v[14:15], v[32:33], v[2:3]
	v_pk_fma_f32 v[34:35], v[14:15], v[34:35], v[4:5]
	s_add_u32 s2, s2, s31
	s_addc_u32 s3, s3, s29
	s_waitcnt vmcnt(18)
	v_cvt_pk_bf16_f32 v6, v24, v25
	v_cvt_pk_bf16_f32 v7, v26, v27
	v_cvt_pk_bf16_f32 v8, v28, v29
	v_cvt_pk_bf16_f32 v9, v30, v31
	v_cvt_pk_bf16_f32 v10, v32, v33
	v_cvt_pk_bf16_f32 v11, v34, v35
	global_store_dwordx2 v19, v[6:7], s[2:3]
	global_store_dwordx2 v19, v[8:9], s[2:3] offset:2048
	global_store_dwordx2 v20, v[10:11], s[2:3]
	v_pk_fma_f32 v[24:25], v[14:15], v[24:25], v[130:131]
	v_pk_fma_f32 v[26:27], v[14:15], v[26:27], v[132:133]
	v_pk_fma_f32 v[28:29], v[14:15], v[28:29], v[134:135]
	v_pk_fma_f32 v[30:31], v[14:15], v[30:31], v[136:137]
	v_pk_fma_f32 v[32:33], v[14:15], v[32:33], v[138:139]
	v_pk_fma_f32 v[34:35], v[14:15], v[34:35], v[140:141]
	s_add_u32 s2, s2, s31
	s_addc_u32 s3, s3, s29
	s_waitcnt vmcnt(15)
	v_cvt_pk_bf16_f32 v6, v24, v25
	v_cvt_pk_bf16_f32 v7, v26, v27
	v_cvt_pk_bf16_f32 v8, v28, v29
	v_cvt_pk_bf16_f32 v9, v30, v31
	v_cvt_pk_bf16_f32 v10, v32, v33
	v_cvt_pk_bf16_f32 v11, v34, v35
	global_store_dwordx2 v19, v[6:7], s[2:3]
	global_store_dwordx2 v19, v[8:9], s[2:3] offset:2048
	global_store_dwordx2 v20, v[10:11], s[2:3]
	v_pk_fma_f32 v[24:25], v[14:15], v[24:25], v[142:143]
	v_pk_fma_f32 v[26:27], v[14:15], v[26:27], v[144:145]
	v_pk_fma_f32 v[28:29], v[14:15], v[28:29], v[146:147]
	v_pk_fma_f32 v[30:31], v[14:15], v[30:31], v[148:149]
	v_pk_fma_f32 v[32:33], v[14:15], v[32:33], v[150:151]
	v_pk_fma_f32 v[34:35], v[14:15], v[34:35], v[152:153]
	s_add_u32 s2, s2, s31
	s_addc_u32 s3, s3, s29
